# meta-row LayerNorm tasks: the 64 partial-statistics loads gathered 16 at a time with counted waits (same summation order) instead of one load + full wait each
# speedup vs baseline: 1.0230x; 1.0089x over previous
.LBB0_875:
	v_lshl_add_u64 v[20:21], v[10:11], 0, s[0:1]
	v_add_co_u32_e32 v20, vcc, 0x3b0a0000, v20
	s_add_u32 s0, s0, 0x800
	s_nop 0
	v_addc_co_u32_e32 v21, vcc, 0, v21, vcc
	global_load_dwordx2 v[152:153], v[20:21], off offset:512
	global_load_dwordx2 v[154:155], v[20:21], off offset:640
	global_load_dwordx2 v[156:157], v[20:21], off offset:768
	global_load_dwordx2 v[158:159], v[20:21], off offset:896
	global_load_dwordx2 v[160:161], v[20:21], off offset:1024
	global_load_dwordx2 v[162:163], v[20:21], off offset:1152
	global_load_dwordx2 v[164:165], v[20:21], off offset:1280
	global_load_dwordx2 v[166:167], v[20:21], off offset:1408
	global_load_dwordx2 v[168:169], v[20:21], off offset:1536
	global_load_dwordx2 v[170:171], v[20:21], off offset:1664
	global_load_dwordx2 v[172:173], v[20:21], off offset:1792
	global_load_dwordx2 v[174:175], v[20:21], off offset:1920
	global_load_dwordx2 v[176:177], v[20:21], off offset:2048
	global_load_dwordx2 v[178:179], v[20:21], off offset:2176
	global_load_dwordx2 v[180:181], v[20:21], off offset:2304
	global_load_dwordx2 v[182:183], v[20:21], off offset:2432
	s_addc_u32 s1, s1, 0
	s_cmpk_eq_i32 s0, 0x2000
	s_waitcnt vmcnt(15)
	v_pk_add_f32 v[12:13], v[12:13], v[152:153]
	s_waitcnt vmcnt(14)
	v_pk_add_f32 v[12:13], v[12:13], v[154:155]
	s_waitcnt vmcnt(13)
	v_pk_add_f32 v[12:13], v[12:13], v[156:157]
	s_waitcnt vmcnt(12)
	v_pk_add_f32 v[12:13], v[12:13], v[158:159]
	s_waitcnt vmcnt(11)
	v_pk_add_f32 v[12:13], v[12:13], v[160:161]
	s_waitcnt vmcnt(10)
	v_pk_add_f32 v[12:13], v[12:13], v[162:163]
	s_waitcnt vmcnt(9)
	v_pk_add_f32 v[12:13], v[12:13], v[164:165]
	s_waitcnt vmcnt(8)
	v_pk_add_f32 v[12:13], v[12:13], v[166:167]
	s_waitcnt vmcnt(7)
	v_pk_add_f32 v[12:13], v[12:13], v[168:169]
	s_waitcnt vmcnt(6)
	v_pk_add_f32 v[12:13], v[12:13], v[170:171]
	s_waitcnt vmcnt(5)
	v_pk_add_f32 v[12:13], v[12:13], v[172:173]
	s_waitcnt vmcnt(4)
	v_pk_add_f32 v[12:13], v[12:13], v[174:175]
	s_waitcnt vmcnt(3)
	v_pk_add_f32 v[12:13], v[12:13], v[176:177]
	s_waitcnt vmcnt(2)
	v_pk_add_f32 v[12:13], v[12:13], v[178:179]
	s_waitcnt vmcnt(1)
	v_pk_add_f32 v[12:13], v[12:13], v[180:181]
	s_waitcnt vmcnt(0)
	v_pk_add_f32 v[12:13], v[12:13], v[182:183]
	s_cbranch_scc0 .LBB0_875
	s_mov_b32 s0, 0x3a000000
	v_pk_mul_f32 v[32:33], v[12:13], s[0:1] op_sel_hi:[1,0]
	s_mov_b32 s0, 0x800000
	v_fma_f32 v0, -v32, v32, v33
	v_max_f32_e32 v0, 0, v0
	v_add_f32_e32 v0, 0x3727c5ac, v0
	v_cmp_gt_f32_e32 vcc, s0, v0
	v_mul_f32_e32 v10, 0x4b800000, v0
	v_lshlrev_b64 v[24:25], 2, v[14:15]
	v_cndmask_b32_e32 v0, v0, v10, vcc
	v_rsq_f32_e32 v0, v0
	v_lshl_add_u64 v[20:21], v[130:131], 0, v[24:25]
	v_lshl_add_u64 v[28:29], v[132:133], 0, v[24:25]
	v_sub_f32_e32 v7, v7, v32
	v_mul_f32_e32 v10, 0x45800000, v0
	v_cndmask_b32_e32 v0, v0, v10, vcc
	global_load_dwordx4 v[10:13], v[20:21], off offset:16
	s_nop 0
	global_load_dwordx4 v[20:23], v[20:21], off
	s_nop 0
	global_load_dwordx4 v[24:27], v[28:29], off offset:16
	s_nop 0
	global_load_dwordx4 v[28:31], v[28:29], off
	v_sub_f32_e32 v6, v6, v32
	v_pk_mul_f32 v[6:7], v[6:7], v[0:1] op_sel_hi:[1,0]
	v_sub_f32_e32 v9, v9, v32
	v_sub_f32_e32 v8, v8, v32
	v_sub_f32_e32 v3, v3, v32
	v_sub_f32_e32 v2, v2, v32
	v_sub_f32_e32 v5, v5, v32
	v_sub_f32_e32 v4, v4, v32
	v_pk_mul_f32 v[8:9], v[8:9], v[0:1] op_sel_hi:[1,0]
	v_pk_mul_f32 v[4:5], v[4:5], v[0:1] op_sel_hi:[1,0]
	v_pk_mul_f32 v[2:3], v[2:3], v[0:1] op_sel_hi:[1,0]
	s_waitcnt vmcnt(1)
	v_pk_fma_f32 v[10:11], v[4:5], v[10:11], v[24:25]
	s_waitcnt vmcnt(0)
	v_pk_fma_f32 v[6:7], v[6:7], v[20:21], v[28:29]
	v_lshlrev_b32_e32 v20, 11, v18
	v_or_b32_e32 v0, 0x38000, v20
	v_pk_fma_f32 v[8:9], v[8:9], v[22:23], v[30:31]
	v_pk_fma_f32 v[12:13], v[2:3], v[12:13], v[26:27]
	v_lshl_add_u64 v[18:19], v[0:1], 0, v[14:15]
	v_cvt_pk_bf16_f32 v2, v6, v7
	v_cvt_pk_bf16_f32 v3, v8, v9
	v_cvt_pk_bf16_f32 v4, v10, v11
	v_cvt_pk_bf16_f32 v5, v12, v13
	global_store_dwordx4 v[16:17], v[6:9], off
	global_store_dwordx4 v[16:17], v[10:13], off offset:16
	v_lshl_add_u64 v[16:17], v[18:19], 1, s[52:53]
	v_or_b32_e32 v0, 0x478000, v20
	global_store_dwordx4 v[16:17], v[2:5], off
	v_lshl_add_u64 v[16:17], v[0:1], 0, v[14:15]
	v_lshl_add_u64 v[18:19], v[16:17], 2, s[28:29]
	v_lshl_add_u64 v[16:17], v[16:17], 1, s[52:53]
	v_or_b32_e32 v0, 0x8b8000, v20
	global_store_dwordx4 v[18:19], v[6:9], off
	global_store_dwordx4 v[18:19], v[10:13], off offset:16
	global_store_dwordx4 v[16:17], v[2:5], off
	v_lshl_add_u64 v[16:17], v[0:1], 0, v[14:15]
	v_or_b32_e32 v0, 0xcf8000, v20
	v_lshl_add_u64 v[18:19], v[16:17], 2, s[28:29]
	v_lshl_add_u64 v[16:17], v[16:17], 1, s[52:53]
	v_lshl_add_u64 v[14:15], v[0:1], 0, v[14:15]
	global_store_dwordx4 v[18:19], v[6:9], off
	global_store_dwordx4 v[18:19], v[10:13], off offset:16
	global_store_dwordx4 v[16:17], v[2:5], off
	v_lshl_add_u64 v[16:17], v[14:15], 2, s[28:29]
	global_store_dwordx4 v[16:17], v[6:9], off
	global_store_dwordx4 v[16:17], v[10:13], off offset:16
	s_nop 0
	v_lshl_add_u64 v[6:7], v[14:15], 1, s[52:53]
	global_store_dwordx4 v[6:7], v[2:5], off

.LBB0_1289:
	v_lshl_add_u64 v[20:21], v[10:11], 0, s[0:1]
	v_add_co_u32_e32 v20, vcc, 0x3b0a0000, v20
	s_add_u32 s0, s0, 0x800
	s_nop 0
	v_addc_co_u32_e32 v21, vcc, 0, v21, vcc
	global_load_dwordx2 v[152:153], v[20:21], off offset:512
	global_load_dwordx2 v[154:155], v[20:21], off offset:640
	global_load_dwordx2 v[156:157], v[20:21], off offset:768
	global_load_dwordx2 v[158:159], v[20:21], off offset:896
	global_load_dwordx2 v[160:161], v[20:21], off offset:1024
	global_load_dwordx2 v[162:163], v[20:21], off offset:1152
	global_load_dwordx2 v[164:165], v[20:21], off offset:1280
	global_load_dwordx2 v[166:167], v[20:21], off offset:1408
	global_load_dwordx2 v[168:169], v[20:21], off offset:1536
	global_load_dwordx2 v[170:171], v[20:21], off offset:1664
	global_load_dwordx2 v[172:173], v[20:21], off offset:1792
	global_load_dwordx2 v[174:175], v[20:21], off offset:1920
	global_load_dwordx2 v[176:177], v[20:21], off offset:2048
	global_load_dwordx2 v[178:179], v[20:21], off offset:2176
	global_load_dwordx2 v[180:181], v[20:21], off offset:2304
	global_load_dwordx2 v[182:183], v[20:21], off offset:2432
	s_addc_u32 s1, s1, 0
	s_cmpk_eq_i32 s0, 0x2000
	s_waitcnt vmcnt(15)
	v_pk_add_f32 v[12:13], v[12:13], v[152:153]
	s_waitcnt vmcnt(14)
	v_pk_add_f32 v[12:13], v[12:13], v[154:155]
	s_waitcnt vmcnt(13)
	v_pk_add_f32 v[12:13], v[12:13], v[156:157]
	s_waitcnt vmcnt(12)
	v_pk_add_f32 v[12:13], v[12:13], v[158:159]
	s_waitcnt vmcnt(11)
	v_pk_add_f32 v[12:13], v[12:13], v[160:161]
	s_waitcnt vmcnt(10)
	v_pk_add_f32 v[12:13], v[12:13], v[162:163]
	s_waitcnt vmcnt(9)
	v_pk_add_f32 v[12:13], v[12:13], v[164:165]
	s_waitcnt vmcnt(8)
	v_pk_add_f32 v[12:13], v[12:13], v[166:167]
	s_waitcnt vmcnt(7)
	v_pk_add_f32 v[12:13], v[12:13], v[168:169]
	s_waitcnt vmcnt(6)
	v_pk_add_f32 v[12:13], v[12:13], v[170:171]
	s_waitcnt vmcnt(5)
	v_pk_add_f32 v[12:13], v[12:13], v[172:173]
	s_waitcnt vmcnt(4)
	v_pk_add_f32 v[12:13], v[12:13], v[174:175]
	s_waitcnt vmcnt(3)
	v_pk_add_f32 v[12:13], v[12:13], v[176:177]
	s_waitcnt vmcnt(2)
	v_pk_add_f32 v[12:13], v[12:13], v[178:179]
	s_waitcnt vmcnt(1)
	v_pk_add_f32 v[12:13], v[12:13], v[180:181]
	s_waitcnt vmcnt(0)
	v_pk_add_f32 v[12:13], v[12:13], v[182:183]
	s_cbranch_scc0 .LBB0_1289
	s_mov_b32 s0, 0x3a000000
	v_pk_mul_f32 v[32:33], v[12:13], s[0:1] op_sel_hi:[1,0]
	s_mov_b32 s0, 0x800000
	v_fma_f32 v0, -v32, v32, v33
	v_max_f32_e32 v0, 0, v0
	v_add_f32_e32 v0, 0x3727c5ac, v0
	v_cmp_gt_f32_e32 vcc, s0, v0
	v_mul_f32_e32 v10, 0x4b800000, v0
	v_lshlrev_b64 v[24:25], 2, v[14:15]
	v_cndmask_b32_e32 v0, v0, v10, vcc
	v_rsq_f32_e32 v0, v0
	v_lshl_add_u64 v[20:21], v[132:133], 0, v[24:25]
	v_lshl_add_u64 v[28:29], v[130:131], 0, v[24:25]
	v_sub_f32_e32 v7, v7, v32
	v_mul_f32_e32 v10, 0x45800000, v0
	v_cndmask_b32_e32 v0, v0, v10, vcc
	global_load_dwordx4 v[10:13], v[20:21], off offset:16
	s_nop 0
	global_load_dwordx4 v[20:23], v[20:21], off
	s_nop 0
	global_load_dwordx4 v[24:27], v[28:29], off offset:16
	s_nop 0
	global_load_dwordx4 v[28:31], v[28:29], off
	v_sub_f32_e32 v6, v6, v32
	v_pk_mul_f32 v[6:7], v[6:7], v[0:1] op_sel_hi:[1,0]
	v_sub_f32_e32 v9, v9, v32
	v_sub_f32_e32 v8, v8, v32
	v_sub_f32_e32 v3, v3, v32
	v_sub_f32_e32 v2, v2, v32
	v_sub_f32_e32 v5, v5, v32
	v_sub_f32_e32 v4, v4, v32
	v_pk_mul_f32 v[8:9], v[8:9], v[0:1] op_sel_hi:[1,0]
	v_pk_mul_f32 v[4:5], v[4:5], v[0:1] op_sel_hi:[1,0]
	v_pk_mul_f32 v[2:3], v[2:3], v[0:1] op_sel_hi:[1,0]
	s_waitcnt vmcnt(1)
	v_pk_fma_f32 v[10:11], v[4:5], v[10:11], v[24:25]
	s_waitcnt vmcnt(0)
	v_pk_fma_f32 v[6:7], v[6:7], v[20:21], v[28:29]
	v_lshlrev_b32_e32 v20, 11, v18
	v_or_b32_e32 v0, 0x38000, v20
	v_pk_fma_f32 v[8:9], v[8:9], v[22:23], v[30:31]
	v_pk_fma_f32 v[12:13], v[2:3], v[12:13], v[26:27]
	v_lshl_add_u64 v[18:19], v[0:1], 0, v[14:15]
	v_cvt_pk_bf16_f32 v2, v6, v7
	v_cvt_pk_bf16_f32 v3, v8, v9
	v_cvt_pk_bf16_f32 v4, v10, v11
	v_cvt_pk_bf16_f32 v5, v12, v13
	global_store_dwordx4 v[16:17], v[6:9], off
	global_store_dwordx4 v[16:17], v[10:13], off offset:16
	v_lshl_add_u64 v[16:17], v[18:19], 1, s[26:27]
	v_or_b32_e32 v0, 0x478000, v20
	global_store_dwordx4 v[16:17], v[2:5], off
	v_lshl_add_u64 v[16:17], v[0:1], 0, v[14:15]
	v_lshl_add_u64 v[18:19], v[16:17], 2, s[28:29]
	v_lshl_add_u64 v[16:17], v[16:17], 1, s[26:27]
	v_or_b32_e32 v0, 0x8b8000, v20
	global_store_dwordx4 v[18:19], v[6:9], off
	global_store_dwordx4 v[18:19], v[10:13], off offset:16
	global_store_dwordx4 v[16:17], v[2:5], off
	v_lshl_add_u64 v[16:17], v[0:1], 0, v[14:15]
	v_or_b32_e32 v0, 0xcf8000, v20
	v_lshl_add_u64 v[18:19], v[16:17], 2, s[28:29]
	v_lshl_add_u64 v[16:17], v[16:17], 1, s[26:27]
	v_lshl_add_u64 v[14:15], v[0:1], 0, v[14:15]
	global_store_dwordx4 v[18:19], v[6:9], off
	global_store_dwordx4 v[18:19], v[10:13], off offset:16
	global_store_dwordx4 v[16:17], v[2:5], off
	v_lshl_add_u64 v[16:17], v[14:15], 2, s[28:29]
	global_store_dwordx4 v[16:17], v[6:9], off
	global_store_dwordx4 v[16:17], v[10:13], off offset:16
	s_nop 0
	v_lshl_add_u64 v[6:7], v[14:15], 1, s[26:27]
	global_store_dwordx4 v[6:7], v[2:5], off
